# phase 0 row pass: next row's x lines touched one trip ahead
# speedup vs baseline: 1.0224x; 1.0023x over previous
.LBB0_637:
	v_mov_b32_e32 v0, v204
	v_readlane_b32 s2, v254, 26
	v_lshlrev_b32_e32 v0, 2, v0
	v_and_b32_e32 v19, 0xfc, v0
	v_readlane_b32 s3, v254, 27
	v_ashrrev_i32_e32 v21, 31, v20
	s_andn2_b64 vcc, exec, s[2:3]
	v_lshlrev_b32_e32 v16, 2, v19
	s_cbranch_vccnz .LBB0_650
	v_readlane_b32 s4, v252, 8
	v_lshlrev_b64 v[0:1], 12, v[20:21]
	v_readlane_b32 s5, v252, 9
	v_mov_b32_e32 v17, v189
	s_nop 0
	v_lshl_add_u64 v[0:1], s[4:5], 0, v[0:1]
	v_lshl_add_u64 v[0:1], v[0:1], 0, v[16:17]
	global_load_dwordx4 v[12:15], v[0:1], off
	global_load_dwordx4 v[8:11], v[0:1], off offset:1024
	global_load_dwordx4 v[4:7], v[0:1], off offset:2048
	s_nop 0
	global_load_dwordx4 v[0:3], v[0:1], off offset:3072
	s_add_i32 vcc_lo, s0, s96
	s_cmpk_lt_i32 vcc_lo, 0x1000
	s_cbranch_scc0 .Lrp0_notouch
	v_add_u32_e32 v30, s70, v20
	v_ashrrev_i32_e32 v31, 31, v30
	v_lshlrev_b64 v[30:31], 12, v[30:31]
	v_lshl_add_u64 v[30:31], s[4:5], 0, v[30:31]
	v_lshl_add_u64 v[30:31], v[30:31], 0, v[16:17]
	global_load_dword v48, v[30:31], off
	global_load_dword v48, v[30:31], off offset:1024
	global_load_dword v48, v[30:31], off offset:2048
	global_load_dword v48, v[30:31], off offset:3072
.Lrp0_notouch:
	v_readlane_b32 s6, v252, 10
	v_readlane_b32 s7, v252, 11
	v_lshlrev_b64 v[22:23], 11, v[20:21]
	s_cbranch_execnz .LBB0_640
